# v63 + mLSTM chunk prologue: wave 0 at priority 2 during its serial gate prefix scan
# baseline (speedup 1.0000x reference)
; __device__ __forceinline__ void mlstm_item(const P& p, const Ctx& c, int seg, int w, bool save) {
;     ...
;         if (c.wv == 0) {
;             float bc = plf;
; #pragma unroll
;             for (int o = 1; o < 64; o <<= 1) { const float t = __shfl_up(bc, o); if (c.lane >= o) bc += t; }
;             const float bl = __shfl(bc, 63);
;             bcum[c.lane] = bc; ipr[c.lane] = pip; wgt[c.lane] = __expf(bl - bc + pip); gin[c.lane] = __expf(bc);
;             if (c.lane == 0) gtotp[0] = __expf(bl);
.LBB0_365:
	v_mov_b32_e32 v181, v170
	v_mov_b32_e32 v180, v174
	v_mov_b32_e32 v191, v176
	s_waitcnt lgkmcnt(0)
	s_barrier
	v_cndmask_b32_e64 v4, 0, 1, s[54:55]
	v_cmp_ne_u32_e64 s[16:17], 1, v4
	s_andn2_b64 vcc, exec, s[54:55]
	s_cbranch_vccnz .LBB0_369
	s_setprio 2
	s_waitcnt vmcnt(7)
	v_mov_b32_e32 v82, v3
	s_nop 1
	v_add_f32_dpp v82, v82, v82 row_shr:1 row_mask:0xf bank_mask:0xf bound_ctrl:1
	s_nop 1
	v_add_f32_dpp v82, v82, v82 row_shr:2 row_mask:0xf bank_mask:0xf bound_ctrl:1
	s_nop 1
	v_add_f32_dpp v82, v82, v82 row_shr:4 row_mask:0xf bank_mask:0xf bound_ctrl:1
	s_nop 1
	v_add_f32_dpp v82, v82, v82 row_shr:8 row_mask:0xf bank_mask:0xf bound_ctrl:1
	s_nop 1
	v_add_f32_dpp v82, v82, v82 row_bcast:15 row_mask:0xa bank_mask:0xf
	s_nop 1
	v_add_f32_dpp v82, v82, v82 row_bcast:31 row_mask:0xc bank_mask:0xf
	s_nop 1
	v_readlane_b32 s86, v82, 63
	s_nop 1
	v_mov_b32_e32 v4, s86
	ds_write_b32 v179, v82
	s_waitcnt vmcnt(6)
	ds_write_b32 v187, v177
	s_waitcnt lgkmcnt(2)
	v_sub_f32_e32 v83, v4, v82
	v_add_f32_e32 v83, v177, v83
	v_mul_f32_e32 v83, 0x3fb8aa3b, v83
	v_mul_f32_e32 v82, 0x3fb8aa3b, v82
	v_exp_f32_e32 v83, v83
	v_exp_f32_e32 v82, v82
	ds_write_b32 v188, v83
	ds_write_b32 v189, v82
	s_and_saveexec_b64 s[86:87], s[4:5]
	s_cbranch_execz .LBB0_368
	v_mul_f32_e32 v4, 0x3fb8aa3b, v4
	v_exp_f32_e32 v4, v4
	v_mov_b32_e32 v82, s62
	ds_write_b32 v82, v4

; __device__ __forceinline__ bf16_t f2bf(float f) { const __bf16 r = (__bf16)f; bf16_t u; __builtin_memcpy(&u, &r, 2); return u; }
; __device__ __forceinline__ void mlstm_item(const P& p, const Ctx& c, int seg, int w, bool save) {
;     ...
; #pragma unroll
;         for (int j = 0; j < 12; ++j)
; #pragma unroll
;             for (int jj = 0; jj < 4; ++jj) Cimg[(e16 * 16 + quad * 4 + jj) * 392 + (2 * j + par) * 16 + l15] = f2bf(C[j][jj]);
.LBB0_369:
	s_setprio 0
	v_lshlrev_b32_e32 v192, 2, v181
	v_add_u32_e32 v4, s79, v192
	v_lshlrev_b32_e32 v82, 1, v180
	v_mul_lo_u32 v4, v4, s33
	v_add3_u32 v4, s97, v82, v4
	v_and_b32_e32 v242, 1, v180
	v_cmp_ne_u32_e32 vcc, 0, v242
	v_mov_b32_e32 v243, 0x5040100
	v_mov_b32_e32 v244, 0x3020706
	v_mul_u32_u24_e32 v242, 0x61e, v242
	v_cndmask_b32_e32 v243, v243, v244, vcc
	v_add_u32_e32 v242, v4, v242
	s_waitcnt vmcnt(51)
	v_cvt_pk_bf16_f32 v234, v6, v8
	v_cvt_pk_bf16_f32 v235, v7, v9
	s_nop 0
	v_mov_b32_dpp v236, v234 quad_perm:[1,0,3,2] row_mask:0xf bank_mask:0xf bound_ctrl:1
	v_mov_b32_dpp v237, v235 quad_perm:[1,0,3,2] row_mask:0xf bank_mask:0xf bound_ctrl:1
	v_perm_b32 v238, v236, v234, v243
	v_perm_b32 v239, v237, v235, v243
	ds_write_b32 v242, v238
	ds_write_b32 v242, v239 offset:784
	s_waitcnt vmcnt(47)
	v_cvt_pk_bf16_f32 v234, v14, v16
	v_cvt_pk_bf16_f32 v235, v15, v17
	s_nop 0
	v_mov_b32_dpp v236, v234 quad_perm:[1,0,3,2] row_mask:0xf bank_mask:0xf bound_ctrl:1
	v_mov_b32_dpp v237, v235 quad_perm:[1,0,3,2] row_mask:0xf bank_mask:0xf bound_ctrl:1
	v_perm_b32 v238, v236, v234, v243
	v_perm_b32 v239, v237, v235, v243
	ds_write_b32 v242, v238 offset:64
	ds_write_b32 v242, v239 offset:848
	s_waitcnt vmcnt(43)
	v_cvt_pk_bf16_f32 v234, v22, v24
	v_cvt_pk_bf16_f32 v235, v23, v25
	s_nop 0
	v_mov_b32_dpp v236, v234 quad_perm:[1,0,3,2] row_mask:0xf bank_mask:0xf bound_ctrl:1
	v_mov_b32_dpp v237, v235 quad_perm:[1,0,3,2] row_mask:0xf bank_mask:0xf bound_ctrl:1
	v_perm_b32 v238, v236, v234, v243
	v_perm_b32 v239, v237, v235, v243
	ds_write_b32 v242, v238 offset:128
	ds_write_b32 v242, v239 offset:912
	s_waitcnt vmcnt(39)
	v_cvt_pk_bf16_f32 v234, v26, v28
	v_cvt_pk_bf16_f32 v235, v27, v29
	s_nop 0
	v_mov_b32_dpp v236, v234 quad_perm:[1,0,3,2] row_mask:0xf bank_mask:0xf bound_ctrl:1
	v_mov_b32_dpp v237, v235 quad_perm:[1,0,3,2] row_mask:0xf bank_mask:0xf bound_ctrl:1
	v_perm_b32 v238, v236, v234, v243
	v_perm_b32 v239, v237, v235, v243
	ds_write_b32 v242, v238 offset:192
	ds_write_b32 v242, v239 offset:976
	s_waitcnt vmcnt(35)
	v_cvt_pk_bf16_f32 v234, v10, v12
	v_cvt_pk_bf16_f32 v235, v11, v13
	s_nop 0
	v_mov_b32_dpp v236, v234 quad_perm:[1,0,3,2] row_mask:0xf bank_mask:0xf bound_ctrl:1
	v_mov_b32_dpp v237, v235 quad_perm:[1,0,3,2] row_mask:0xf bank_mask:0xf bound_ctrl:1
	v_perm_b32 v238, v236, v234, v243
	v_perm_b32 v239, v237, v235, v243
	ds_write_b32 v242, v238 offset:256
	ds_write_b32 v242, v239 offset:1040
	s_waitcnt vmcnt(31)
	v_cvt_pk_bf16_f32 v234, v18, v20
	v_cvt_pk_bf16_f32 v235, v19, v21
	s_nop 0
	v_mov_b32_dpp v236, v234 quad_perm:[1,0,3,2] row_mask:0xf bank_mask:0xf bound_ctrl:1
	v_mov_b32_dpp v237, v235 quad_perm:[1,0,3,2] row_mask:0xf bank_mask:0xf bound_ctrl:1
	v_perm_b32 v238, v236, v234, v243
	v_perm_b32 v239, v237, v235, v243
	ds_write_b32 v242, v238 offset:320
	ds_write_b32 v242, v239 offset:1104
	s_waitcnt vmcnt(27)
	v_cvt_pk_bf16_f32 v234, v30, v32
	v_cvt_pk_bf16_f32 v235, v31, v33
	s_nop 0
	v_mov_b32_dpp v236, v234 quad_perm:[1,0,3,2] row_mask:0xf bank_mask:0xf bound_ctrl:1
	v_mov_b32_dpp v237, v235 quad_perm:[1,0,3,2] row_mask:0xf bank_mask:0xf bound_ctrl:1
	v_perm_b32 v238, v236, v234, v243
	v_perm_b32 v239, v237, v235, v243
	ds_write_b32 v242, v238 offset:384
	ds_write_b32 v242, v239 offset:1168
	s_waitcnt vmcnt(23)
	v_cvt_pk_bf16_f32 v234, v34, v36
	v_cvt_pk_bf16_f32 v235, v35, v37
	s_nop 0
	v_mov_b32_dpp v236, v234 quad_perm:[1,0,3,2] row_mask:0xf bank_mask:0xf bound_ctrl:1
	v_mov_b32_dpp v237, v235 quad_perm:[1,0,3,2] row_mask:0xf bank_mask:0xf bound_ctrl:1
	v_perm_b32 v238, v236, v234, v243
	v_perm_b32 v239, v237, v235, v243
	ds_write_b32 v242, v238 offset:448
	ds_write_b32 v242, v239 offset:1232
	s_waitcnt vmcnt(19)
	v_cvt_pk_bf16_f32 v234, v38, v40
	v_cvt_pk_bf16_f32 v235, v39, v41
	s_nop 0
	v_mov_b32_dpp v236, v234 quad_perm:[1,0,3,2] row_mask:0xf bank_mask:0xf bound_ctrl:1
	v_mov_b32_dpp v237, v235 quad_perm:[1,0,3,2] row_mask:0xf bank_mask:0xf bound_ctrl:1
	v_perm_b32 v238, v236, v234, v243
	v_perm_b32 v239, v237, v235, v243
	ds_write_b32 v242, v238 offset:512
	ds_write_b32 v242, v239 offset:1296
	s_waitcnt vmcnt(15)
	v_cvt_pk_bf16_f32 v234, v42, v44
	v_cvt_pk_bf16_f32 v235, v43, v45
	s_nop 0
	v_mov_b32_dpp v236, v234 quad_perm:[1,0,3,2] row_mask:0xf bank_mask:0xf bound_ctrl:1
	v_mov_b32_dpp v237, v235 quad_perm:[1,0,3,2] row_mask:0xf bank_mask:0xf bound_ctrl:1
	v_perm_b32 v238, v236, v234, v243
	v_perm_b32 v239, v237, v235, v243
	ds_write_b32 v242, v238 offset:576
	ds_write_b32 v242, v239 offset:1360
	s_waitcnt vmcnt(11)
	v_cvt_pk_bf16_f32 v234, v46, v48
	v_cvt_pk_bf16_f32 v235, v47, v49
	s_nop 0
	v_mov_b32_dpp v236, v234 quad_perm:[1,0,3,2] row_mask:0xf bank_mask:0xf bound_ctrl:1
	v_mov_b32_dpp v237, v235 quad_perm:[1,0,3,2] row_mask:0xf bank_mask:0xf bound_ctrl:1
	v_perm_b32 v238, v236, v234, v243
	v_perm_b32 v239, v237, v235, v243
	ds_write_b32 v242, v238 offset:640
	ds_write_b32 v242, v239 offset:1424
	s_waitcnt vmcnt(7)
	v_cvt_pk_bf16_f32 v234, v54, v56
	v_cvt_pk_bf16_f32 v235, v55, v57
	s_nop 0
	v_mov_b32_dpp v236, v234 quad_perm:[1,0,3,2] row_mask:0xf bank_mask:0xf bound_ctrl:1
	v_mov_b32_dpp v237, v235 quad_perm:[1,0,3,2] row_mask:0xf bank_mask:0xf bound_ctrl:1
	v_perm_b32 v238, v236, v234, v243
	v_perm_b32 v239, v237, v235, v243
	ds_write_b32 v242, v238 offset:704
	ds_write_b32 v242, v239 offset:1488
	v_lshlrev_b32_e32 v4, 3, v191
	v_ashrrev_i32_e32 v82, 3, v191
	v_and_b32_e32 v4, 56, v4
	v_mul_lo_u32 v83, v82, s63
	v_lshlrev_b32_e32 v94, 1, v4
	v_add3_u32 v84, s28, v83, v94
	v_lshl_add_u32 v4, v4, 2, 0
	s_waitcnt lgkmcnt(0)
	s_barrier
; #define LAS __attribute__((address_space(3)))
; __device__ __forceinline__ unsigned pk2(float lo, float hi) { const bf2_t r = __builtin_convertvector((f32x2){lo, hi}, bf2_t); unsigned u; __builtin_memcpy(&u, &r, 4); return u; }
; __device__ __forceinline__ float bflo(unsigned u) { return __uint_as_float(u << 16); }
; __device__ __forceinline__ float bfhi(unsigned u) { return __uint_as_float(u & 0xFFFF0000u); }
; __device__ __forceinline__ void lds_barrier() { asm volatile("s_waitcnt lgkmcnt(0)" ::: "memory"); __builtin_amdgcn_s_barrier(); asm volatile("" ::: "memory"); }
; __device__ __forceinline__ void mlstm_item(const P& p, const Ctx& c, int seg, int w, bool save) {
;     ...
;     auto gl_chunk = [&](int ch, int tidv) { const int i = tidv >> 3, c8 = (tidv & 7) * 8;
;         pvt = *(const u32x4*)(VT + ((size_t)(b * 4 + h) * 384 + sl * 64 + i) * SEGT + ch * 64 + c8);
;         if (c.wv == 0) { plf = LOGF[(b * 4 + h) * SEGT + ch * 64 + c.lane]; pip = IPRE[(b * 4 + h) * SEGT + ch * 64 + c.lane]; } };
;     ...
;         lds_barrier();
;         { const int i = tidv >> 3, c8 = (tidv & 7) * 8;
;           const u32x4 raw = pvt;
;           *(LAS u32x4*)(VTs + i * 72 + c8) = raw;
;           const f32x4 w0 = *(const LAS f32x4*)(wgt + c8), w1 = *(const LAS f32x4*)(wgt + c8 + 4);
;           u32x4 sw; sw.x = pk2(bflo(raw.x) * w0[0], bfhi(raw.x) * w0[1]); sw.y = pk2(bflo(raw.y) * w0[2], bfhi(raw.y) * w0[3]);
;           sw.z = pk2(bflo(raw.z) * w1[0], bfhi(raw.z) * w1[1]); sw.w = pk2(bflo(raw.w) * w1[2], bfhi(raw.w) * w1[3]);
;           *(LAS u32x4*)(VWs + i * 72 + c8) = sw; }
;         if (ch + 1 < 8) gl_chunk(ch + 1, tidv);
	s_waitcnt vmcnt(6)
	ds_write_b128 v84, v[50:53]
	v_add_u32_e32 v4, 0x20200, v4
	ds_read_b128 v[84:87], v4
	ds_read_b128 v[88:91], v4 offset:16
	v_lshlrev_b32_e32 v92, 16, v50
	v_and_b32_e32 v93, 0xffff0000, v50
	s_cmpk_lg_i32 s84, 0x200
	s_waitcnt lgkmcnt(1)
	v_pk_mul_f32 v[84:85], v[84:85], v[92:93]
	v_lshlrev_b32_e32 v92, 16, v51
	v_and_b32_e32 v93, 0xffff0000, v51
	v_pk_mul_f32 v[86:87], v[86:87], v[92:93]
	v_cvt_pk_bf16_f32 v84, v84, v85
	v_cvt_pk_bf16_f32 v85, v86, v87
	v_lshlrev_b32_e32 v86, 16, v52
	v_and_b32_e32 v87, 0xffff0000, v52
	s_waitcnt lgkmcnt(0)
	v_pk_mul_f32 v[86:87], v[88:89], v[86:87]
	v_lshlrev_b32_e32 v88, 16, v53
	v_and_b32_e32 v89, 0xffff0000, v53
	v_pk_mul_f32 v[88:89], v[90:91], v[88:89]
	v_cvt_pk_bf16_f32 v86, v86, v87
	v_cvt_pk_bf16_f32 v87, v88, v89
	v_add3_u32 v4, s29, v83, v94
	s_cselect_b64 s[88:89], -1, 0
	s_cmpk_eq_i32 s84, 0x200
	s_mov_b64 s[90:91], 0x200
	ds_write_b128 v4, v[84:87]
	s_cbranch_scc1 .LBB0_373
	v_ashrrev_i32_e32 v83, 31, v82
	v_lshl_add_u64 v[50:51], s[70:71], 0, v[82:83]
	v_lshlrev_b64 v[50:51], 10, v[50:51]
	v_and_b32_e32 v4, 7, v191
	v_lshl_or_b32 v50, v4, 4, v50
	v_lshl_add_u64 v[50:51], s[82:83], 0, v[50:51]
	global_load_dwordx4 v[50:53], v[50:51], off
	s_and_b64 vcc, exec, s[16:17]
	s_cbranch_vccnz .LBB0_372
	v_add_u32_e32 v82, s84, v2
	v_ashrrev_i32_e32 v83, 31, v82
	v_lshlrev_b64 v[82:83], 2, v[82:83]
	v_lshl_add_u64 v[84:85], s[26:27], 0, v[82:83]
	v_lshl_add_u64 v[82:83], s[30:31], 0, v[82:83]
	global_load_dword v3, v[82:83], off
	global_load_dword v177, v[84:85], off
